# FFN-up GEMM loop: LDS-DMA addresses as SGPR base + 32-bit VGPR offset (16 64-bit VALU adds per K-iteration removed from the load waves)
# speedup vs baseline: 1.0112x; 1.0112x over previous
; #define PG8_STAGE(bufoff, gbase, voff) do { _Pragma("unroll") for (int _i = 0; _i < 2; ++_i) \
;         __builtin_amdgcn_global_load_lds((const unsigned*)((const char*)(gbase) + (voff)[_i]), (LAS unsigned*)(lds + (bufoff) + ldsw + _i * 8192), 16, 0, 0); } while (0)
; #define PG8_LDA(dst, b, h) do { _Pragma("unroll") for (int m = 0; m < 4; ++m) _Pragma("unroll") for (int k = 0; k < 2; ++k) dst[m][k] = *(const LAS bf16x8*)(lds + PG8_SA(b, h) + aoff + m * 2048 + k * 1024); } while (0)
; #define PG8_LDB(dst, b, h) do { _Pragma("unroll") for (int n = 0; n < 2; ++n) _Pragma("unroll") for (int k = 0; k < 2; ++k) dst[n][k] = *(const LAS bf16x8*)(lds + PG8_SB(b, h) + boff + n * 2048 + k * 1024); } while (0)
; #define PG8_MMA(ai, bj, At, Bt) do { __builtin_amdgcn_s_setprio(1); _Pragma("unroll") for (int m = 0; m < 4; ++m) _Pragma("unroll") for (int n = 0; n < 2; ++n) _Pragma("unroll") for (int k = 0; k < 2; ++k) \
;         acc[ai][bj][m][n] = __builtin_amdgcn_mfma_f32_16x16x32_bf16(Bt[n][k], At[m][k], acc[ai][bj][m][n], 0, 0, 0); __builtin_amdgcn_s_setprio(0); } while (0)
; #define PG8_WAIT_V(n) asm volatile("s_waitcnt vmcnt(" #n ")" ::: "memory")
; #define PG8_WAIT_L(n) asm volatile("s_waitcnt lgkmcnt(" #n ")" ::: "memory")
; #define PG8_BAR __builtin_amdgcn_s_barrier()
; #define PG8_SCHED __builtin_amdgcn_sched_barrier(0)
; template <class Epi>
; DI void gemm_phase(LAS unsigned char* lds, const Gemm g, const StaticOrder S, const Epi E) {
;     ...
;             const bool last = (t == nt - 2);
;             const char* a1 = cA + (size_t)(t + 1) * kstep;
;             const char* a2 = last ? nA : cA + (size_t)(t + 2) * kstep; const char* b2 = last ? nB : cB + (size_t)(t + 2) * kstep;
;             const char* a3 = a2 + kstep; const char* b3 = b2 + kstep;
;             PG8_LDB(B0, 0, 0); PG8_LDB(B1, 0, 1); PG8_SCHED; PG8_LDA(At, 0, 0); PG8_STAGE(PG8_SA(1, 1), a1 + hstepA, voffA);
;             PG8_WAIT_V(8); PG8_WAIT_L(0); PG8_BAR; PG8_MMA(0, 0, At, B0); PG8_MMA(0, 1, At, B1); PG8_BAR; PG8_SCHED;
;             PG8_LDA(At, 0, 1); PG8_STAGE(PG8_SB(0, 0), b2, voffB); PG8_STAGE(PG8_SB(0, 1), b2 + hstepB, voffB); PG8_STAGE(PG8_SA(0, 0), a2, voffA);
.LBB0_471:
	s_add_u32 s20, s52, 0xfffc0080
	s_addc_u32 s21, s53, -1
	s_add_i32 s70, 0, 0x10000
	s_cmp_eq_u32 s69, 12
	s_cselect_b32 s55, s47, s21
	s_cselect_b32 s54, s46, s20
	v_add_u32_e32 v138, s70, v142
	s_cselect_b32 s31, s49, s45
	s_cselect_b32 s30, s48, s43
	s_add_i32 s20, 0, 0x14000
	ds_read_b128 v[158:161], v138
	ds_read_b128 v[162:165], v138 offset:1024
	ds_read_b128 v[166:169], v138 offset:2048
	ds_read_b128 v[170:173], v138 offset:3072
	v_add_u32_e32 v138, s20, v142
	ds_read_b128 v[174:177], v138
	ds_read_b128 v[178:181], v138 offset:1024
	ds_read_b128 v[182:185], v138 offset:2048
	ds_read_b128 v[186:189], v138 offset:3072
	s_add_i32 m0, s51, 0xc000
	ds_read_b128 v[190:193], v143
	ds_read_b128 v[194:197], v143 offset:1024
	ds_read_b128 v[220:223], v143 offset:2048
	ds_read_b128 v[230:233], v143 offset:3072
	ds_read_b128 v[234:237], v143 offset:4096
	ds_read_b128 v[238:241], v143 offset:5120
	ds_read_b128 v[242:245], v143 offset:6144
	ds_read_b128 v[246:249], v143 offset:7168
	global_load_lds_dwordx4 v134, s[52:53]
	s_add_i32 m0, s51, 0xe000
	s_nop 0
	global_load_lds_dwordx4 v136, s[52:53]
	s_waitcnt vmcnt(8)
	s_waitcnt lgkmcnt(0)
	s_barrier
	s_setprio 1
	s_waitcnt lgkmcnt(0)
	v_mfma_f32_16x16x32_bf16 v[124:127], v[158:161], v[190:193], v[124:127]
	v_mfma_f32_16x16x32_bf16 v[120:123], v[166:169], v[190:193], v[120:123]
	v_mfma_f32_16x16x32_bf16 v[108:111], v[158:161], v[220:223], v[108:111]
	v_mfma_f32_16x16x32_bf16 v[100:103], v[166:169], v[220:223], v[100:103]
	v_mfma_f32_16x16x32_bf16 v[92:95], v[158:161], v[234:237], v[92:95]
	v_mfma_f32_16x16x32_bf16 v[84:87], v[166:169], v[234:237], v[84:87]
	v_mfma_f32_16x16x32_bf16 v[76:79], v[158:161], v[242:245], v[76:79]
	v_mfma_f32_16x16x32_bf16 v[68:71], v[166:169], v[242:245], v[68:71]
	v_mfma_f32_16x16x32_bf16 v[124:127], v[162:165], v[194:197], v[124:127]
	v_mfma_f32_16x16x32_bf16 v[120:123], v[170:173], v[194:197], v[120:123]
	v_mfma_f32_16x16x32_bf16 v[108:111], v[162:165], v[230:233], v[108:111]
	v_mfma_f32_16x16x32_bf16 v[100:103], v[170:173], v[230:233], v[100:103]
	v_mfma_f32_16x16x32_bf16 v[92:95], v[162:165], v[238:241], v[92:95]
	v_mfma_f32_16x16x32_bf16 v[84:87], v[170:173], v[238:241], v[84:87]
	v_mfma_f32_16x16x32_bf16 v[76:79], v[162:165], v[246:249], v[76:79]
	v_mfma_f32_16x16x32_bf16 v[68:71], v[170:173], v[246:249], v[68:71]
	s_setprio 0
	s_setprio 1
	v_mfma_f32_16x16x32_bf16 v[116:119], v[174:177], v[190:193], v[116:119]
	v_mfma_f32_16x16x32_bf16 v[112:115], v[182:185], v[190:193], v[112:115]
	v_mfma_f32_16x16x32_bf16 v[104:107], v[174:177], v[220:223], v[104:107]
	v_mfma_f32_16x16x32_bf16 v[96:99], v[182:185], v[220:223], v[96:99]
	v_mfma_f32_16x16x32_bf16 v[88:91], v[174:177], v[234:237], v[88:91]
	v_mfma_f32_16x16x32_bf16 v[80:83], v[182:185], v[234:237], v[80:83]
	v_mfma_f32_16x16x32_bf16 v[72:75], v[174:177], v[242:245], v[72:75]
	v_mfma_f32_16x16x32_bf16 v[64:67], v[182:185], v[242:245], v[64:67]
	v_mfma_f32_16x16x32_bf16 v[116:119], v[178:181], v[194:197], v[116:119]
	v_mfma_f32_16x16x32_bf16 v[112:115], v[186:189], v[194:197], v[112:115]
	v_mfma_f32_16x16x32_bf16 v[104:107], v[178:181], v[230:233], v[104:107]
	v_mfma_f32_16x16x32_bf16 v[96:99], v[186:189], v[230:233], v[96:99]
	v_mfma_f32_16x16x32_bf16 v[88:91], v[178:181], v[238:241], v[88:91]
	v_mfma_f32_16x16x32_bf16 v[80:83], v[186:189], v[238:241], v[80:83]
	v_mfma_f32_16x16x32_bf16 v[72:75], v[178:181], v[246:249], v[72:75]
	v_mfma_f32_16x16x32_bf16 v[64:67], v[186:189], v[246:249], v[64:67]
	s_setprio 0
	s_barrier
	s_add_i32 s21, s70, s57
	s_mov_b32 m0, s21
	ds_read_b128 v[190:193], v143 offset:16384
	ds_read_b128 v[194:197], v143 offset:17408
	ds_read_b128 v[220:223], v143 offset:18432
	ds_read_b128 v[230:233], v143 offset:19456
	ds_read_b128 v[234:237], v143 offset:20480
	ds_read_b128 v[238:241], v143 offset:21504
	ds_read_b128 v[242:245], v143 offset:22528
	ds_read_b128 v[246:249], v143 offset:23552
	global_load_lds_dwordx4 v146, s[30:31]
	s_add_i32 m0, s21, 0x2000
	s_add_u32 s70, s30, 0x40000
	s_addc_u32 s71, s31, 0
	s_add_i32 s20, s20, s57
	global_load_lds_dwordx4 v128, s[30:31]
	s_mov_b32 m0, s20
	s_add_u32 s98, s30, 0x80
	s_addc_u32 s99, s31, 0
	global_load_lds_dwordx4 v146, s[70:71]
	s_add_i32 m0, s20, 0x2000
	s_add_u32 s100, s54, 0x80
	global_load_lds_dwordx4 v128, s[70:71]
	s_mov_b32 m0, s51
	s_addc_u32 s101, s55, 0
	global_load_lds_dwordx4 v132, s[54:55]
	s_mov_b32 m0, s61
	s_nop 0
	global_load_lds_dwordx4 v130, s[54:55]
	s_waitcnt vmcnt(8)
	s_waitcnt lgkmcnt(0)
	s_barrier
; #define PG8_STAGE(bufoff, gbase, voff) do { _Pragma("unroll") for (int _i = 0; _i < 2; ++_i) \
;         __builtin_amdgcn_global_load_lds((const unsigned*)((const char*)(gbase) + (voff)[_i]), (LAS unsigned*)(lds + (bufoff) + ldsw + _i * 8192), 16, 0, 0); } while (0)
; #define PG8_LDA(dst, b, h) do { _Pragma("unroll") for (int m = 0; m < 4; ++m) _Pragma("unroll") for (int k = 0; k < 2; ++k) dst[m][k] = *(const LAS bf16x8*)(lds + PG8_SA(b, h) + aoff + m * 2048 + k * 1024); } while (0)
; #define PG8_LDB(dst, b, h) do { _Pragma("unroll") for (int n = 0; n < 2; ++n) _Pragma("unroll") for (int k = 0; k < 2; ++k) dst[n][k] = *(const LAS bf16x8*)(lds + PG8_SB(b, h) + boff + n * 2048 + k * 1024); } while (0)
; #define PG8_MMA(ai, bj, At, Bt) do { __builtin_amdgcn_s_setprio(1); _Pragma("unroll") for (int m = 0; m < 4; ++m) _Pragma("unroll") for (int n = 0; n < 2; ++n) _Pragma("unroll") for (int k = 0; k < 2; ++k) \
;         acc[ai][bj][m][n] = __builtin_amdgcn_mfma_f32_16x16x32_bf16(Bt[n][k], At[m][k], acc[ai][bj][m][n], 0, 0, 0); __builtin_amdgcn_s_setprio(0); } while (0)
; #define PG8_WAIT_V(n) asm volatile("s_waitcnt vmcnt(" #n ")" ::: "memory")
; #define PG8_WAIT_L(n) asm volatile("s_waitcnt lgkmcnt(" #n ")" ::: "memory")
; #define PG8_BAR __builtin_amdgcn_s_barrier()
; #define PG8_SCHED __builtin_amdgcn_sched_barrier(0)
; template <class Epi>
; DI void gemm_phase(LAS unsigned char* lds, const Gemm g, const StaticOrder S, const Epi E) {
;     ...
;             PG8_WAIT_V(8); PG8_WAIT_L(0); PG8_BAR; PG8_MMA(1, 0, At, B0); PG8_MMA(1, 1, At, B1); PG8_BAR; PG8_SCHED;
;             PG8_LDB(B0, 1, 0); PG8_LDB(B1, 1, 1); PG8_SCHED; PG8_LDA(At, 1, 0); PG8_STAGE(PG8_SA(0, 1), a2 + hstepA, voffA);
;             PG8_WAIT_V(8); PG8_WAIT_L(0); PG8_BAR; PG8_MMA(0, 0, At, B0); PG8_MMA(0, 1, At, B1); PG8_BAR; PG8_SCHED;
	s_setprio 1
	s_waitcnt lgkmcnt(0)
	v_mfma_f32_16x16x32_bf16 v[60:63], v[158:161], v[190:193], v[60:63]
	v_mfma_f32_16x16x32_bf16 v[52:55], v[166:169], v[190:193], v[52:55]
	v_mfma_f32_16x16x32_bf16 v[44:47], v[158:161], v[220:223], v[44:47]
	v_mfma_f32_16x16x32_bf16 v[36:39], v[166:169], v[220:223], v[36:39]
	v_mfma_f32_16x16x32_bf16 v[28:31], v[158:161], v[234:237], v[28:31]
	v_mfma_f32_16x16x32_bf16 v[20:23], v[166:169], v[234:237], v[20:23]
	v_mfma_f32_16x16x32_bf16 v[12:15], v[158:161], v[242:245], v[12:15]
	v_mfma_f32_16x16x32_bf16 v[4:7], v[166:169], v[242:245], v[4:7]
	v_mfma_f32_16x16x32_bf16 v[60:63], v[162:165], v[194:197], v[60:63]
	v_mfma_f32_16x16x32_bf16 v[52:55], v[170:173], v[194:197], v[52:55]
	v_mfma_f32_16x16x32_bf16 v[44:47], v[162:165], v[230:233], v[44:47]
	v_mfma_f32_16x16x32_bf16 v[36:39], v[170:173], v[230:233], v[36:39]
	v_mfma_f32_16x16x32_bf16 v[28:31], v[162:165], v[238:241], v[28:31]
	v_mfma_f32_16x16x32_bf16 v[20:23], v[170:173], v[238:241], v[20:23]
	v_mfma_f32_16x16x32_bf16 v[12:15], v[162:165], v[246:249], v[12:15]
	v_mfma_f32_16x16x32_bf16 v[4:7], v[170:173], v[246:249], v[4:7]
	s_setprio 0
	s_setprio 1
	v_mfma_f32_16x16x32_bf16 v[56:59], v[174:177], v[190:193], v[56:59]
	v_mfma_f32_16x16x32_bf16 v[48:51], v[182:185], v[190:193], v[48:51]
	v_mfma_f32_16x16x32_bf16 v[40:43], v[174:177], v[220:223], v[40:43]
	v_mfma_f32_16x16x32_bf16 v[32:35], v[182:185], v[220:223], v[32:35]
	v_mfma_f32_16x16x32_bf16 v[24:27], v[174:177], v[234:237], v[24:27]
	v_mfma_f32_16x16x32_bf16 v[16:19], v[182:185], v[234:237], v[16:19]
	v_mfma_f32_16x16x32_bf16 v[8:11], v[174:177], v[242:245], v[8:11]
	v_mfma_f32_16x16x32_bf16 v[0:3], v[182:185], v[242:245], v[0:3]
	v_mfma_f32_16x16x32_bf16 v[56:59], v[178:181], v[194:197], v[56:59]
	v_mfma_f32_16x16x32_bf16 v[48:51], v[186:189], v[194:197], v[48:51]
	v_mfma_f32_16x16x32_bf16 v[40:43], v[178:181], v[230:233], v[40:43]
	v_mfma_f32_16x16x32_bf16 v[32:35], v[186:189], v[230:233], v[32:35]
	v_mfma_f32_16x16x32_bf16 v[24:27], v[178:181], v[238:241], v[24:27]
	v_mfma_f32_16x16x32_bf16 v[16:19], v[186:189], v[238:241], v[16:19]
	v_mfma_f32_16x16x32_bf16 v[8:11], v[178:181], v[246:249], v[8:11]
	v_mfma_f32_16x16x32_bf16 v[0:3], v[186:189], v[246:249], v[0:3]
	s_setprio 0
	s_barrier
	v_add_u32_e32 v157, s74, v142
	s_add_i32 s20, 0, 0x1c000
	ds_read_b128 v[158:161], v157
	ds_read_b128 v[162:165], v157 offset:1024
	ds_read_b128 v[166:169], v157 offset:2048
	ds_read_b128 v[170:173], v157 offset:3072
	v_add_u32_e32 v157, s20, v142
	ds_read_b128 v[174:177], v157
	ds_read_b128 v[178:181], v157 offset:1024
	ds_read_b128 v[182:185], v157 offset:2048
	ds_read_b128 v[186:189], v157 offset:3072
	s_add_u32 s54, s54, 0x40000
	s_addc_u32 s55, s55, 0
	s_mov_b32 m0, s62
	ds_read_b128 v[190:193], v143 offset:32768
	ds_read_b128 v[194:197], v143 offset:33792
	ds_read_b128 v[220:223], v143 offset:34816
	ds_read_b128 v[230:233], v143 offset:35840
	ds_read_b128 v[234:237], v143 offset:36864
	ds_read_b128 v[238:241], v143 offset:37888
	ds_read_b128 v[242:245], v143 offset:38912
	ds_read_b128 v[246:249], v143 offset:39936
	global_load_lds_dwordx4 v132, s[54:55]
	s_mov_b32 m0, s63
	s_nop 0
	global_load_lds_dwordx4 v130, s[54:55]
	s_waitcnt vmcnt(8)
	s_waitcnt lgkmcnt(0)
	s_barrier
	s_setprio 1
	s_waitcnt lgkmcnt(0)
	v_mfma_f32_16x16x32_bf16 v[124:127], v[158:161], v[190:193], v[124:127]
	v_mfma_f32_16x16x32_bf16 v[120:123], v[166:169], v[190:193], v[120:123]
	v_mfma_f32_16x16x32_bf16 v[108:111], v[158:161], v[220:223], v[108:111]
	v_mfma_f32_16x16x32_bf16 v[100:103], v[166:169], v[220:223], v[100:103]
	v_mfma_f32_16x16x32_bf16 v[92:95], v[158:161], v[234:237], v[92:95]
	v_mfma_f32_16x16x32_bf16 v[84:87], v[166:169], v[234:237], v[84:87]
	v_mfma_f32_16x16x32_bf16 v[76:79], v[158:161], v[242:245], v[76:79]
	v_mfma_f32_16x16x32_bf16 v[68:71], v[166:169], v[242:245], v[68:71]
	v_mfma_f32_16x16x32_bf16 v[124:127], v[162:165], v[194:197], v[124:127]
	v_mfma_f32_16x16x32_bf16 v[120:123], v[170:173], v[194:197], v[120:123]
	v_mfma_f32_16x16x32_bf16 v[108:111], v[162:165], v[230:233], v[108:111]
	v_mfma_f32_16x16x32_bf16 v[100:103], v[170:173], v[230:233], v[100:103]
	v_mfma_f32_16x16x32_bf16 v[92:95], v[162:165], v[238:241], v[92:95]
	v_mfma_f32_16x16x32_bf16 v[84:87], v[170:173], v[238:241], v[84:87]
	v_mfma_f32_16x16x32_bf16 v[76:79], v[162:165], v[246:249], v[76:79]
	v_mfma_f32_16x16x32_bf16 v[68:71], v[170:173], v[246:249], v[68:71]
	s_setprio 0
	s_setprio 1
	v_mfma_f32_16x16x32_bf16 v[116:119], v[174:177], v[190:193], v[116:119]
	v_mfma_f32_16x16x32_bf16 v[112:115], v[182:185], v[190:193], v[112:115]
	v_mfma_f32_16x16x32_bf16 v[104:107], v[174:177], v[220:223], v[104:107]
	v_mfma_f32_16x16x32_bf16 v[96:99], v[182:185], v[220:223], v[96:99]
	v_mfma_f32_16x16x32_bf16 v[88:91], v[174:177], v[234:237], v[88:91]
	v_mfma_f32_16x16x32_bf16 v[80:83], v[182:185], v[234:237], v[80:83]
	v_mfma_f32_16x16x32_bf16 v[72:75], v[174:177], v[242:245], v[72:75]
	v_mfma_f32_16x16x32_bf16 v[64:67], v[182:185], v[242:245], v[64:67]
	v_mfma_f32_16x16x32_bf16 v[116:119], v[178:181], v[194:197], v[116:119]
	v_mfma_f32_16x16x32_bf16 v[112:115], v[186:189], v[194:197], v[112:115]
	v_mfma_f32_16x16x32_bf16 v[104:107], v[178:181], v[230:233], v[104:107]
	v_mfma_f32_16x16x32_bf16 v[96:99], v[186:189], v[230:233], v[96:99]
	v_mfma_f32_16x16x32_bf16 v[88:91], v[178:181], v[238:241], v[88:91]
	v_mfma_f32_16x16x32_bf16 v[80:83], v[186:189], v[238:241], v[80:83]
	v_mfma_f32_16x16x32_bf16 v[72:75], v[178:181], v[246:249], v[72:75]
	v_mfma_f32_16x16x32_bf16 v[64:67], v[186:189], v[246:249], v[64:67]
	s_setprio 0
	s_barrier
; #define PG8_STAGE(bufoff, gbase, voff) do { _Pragma("unroll") for (int _i = 0; _i < 2; ++_i) \
;         __builtin_amdgcn_global_load_lds((const unsigned*)((const char*)(gbase) + (voff)[_i]), (LAS unsigned*)(lds + (bufoff) + ldsw + _i * 8192), 16, 0, 0); } while (0)
; #define PG8_LDA(dst, b, h) do { _Pragma("unroll") for (int m = 0; m < 4; ++m) _Pragma("unroll") for (int k = 0; k < 2; ++k) dst[m][k] = *(const LAS bf16x8*)(lds + PG8_SA(b, h) + aoff + m * 2048 + k * 1024); } while (0)
; #define PG8_MMA(ai, bj, At, Bt) do { __builtin_amdgcn_s_setprio(1); _Pragma("unroll") for (int m = 0; m < 4; ++m) _Pragma("unroll") for (int n = 0; n < 2; ++n) _Pragma("unroll") for (int k = 0; k < 2; ++k) \
;         acc[ai][bj][m][n] = __builtin_amdgcn_mfma_f32_16x16x32_bf16(Bt[n][k], At[m][k], acc[ai][bj][m][n], 0, 0, 0); __builtin_amdgcn_s_setprio(0); } while (0)
; #define PG8_WAIT_V(n) asm volatile("s_waitcnt vmcnt(" #n ")" ::: "memory")
; #define PG8_WAIT_L(n) asm volatile("s_waitcnt lgkmcnt(" #n ")" ::: "memory")
; #define PG8_BAR __builtin_amdgcn_s_barrier()
; #define PG8_SCHED __builtin_amdgcn_sched_barrier(0)
; template <class Epi>
; DI void gemm_phase(LAS unsigned char* lds, const Gemm g, const StaticOrder S, const Epi E) {
;     ...
;             PG8_LDA(At, 1, 1); PG8_STAGE(PG8_SB(1, 0), b3, voffB); PG8_STAGE(PG8_SB(1, 1), b3 + hstepB, voffB); PG8_STAGE(PG8_SA(1, 0), a3, voffA);
;             PG8_WAIT_V(8); PG8_WAIT_L(0); PG8_BAR; PG8_MMA(1, 0, At, B0); PG8_MMA(1, 1, At, B1); PG8_BAR; PG8_SCHED;
;         }
	s_add_i32 s21, s74, s57
	s_mov_b32 m0, s21
	ds_read_b128 v[190:193], v143 offset:49152
	ds_read_b128 v[194:197], v143 offset:50176
	ds_read_b128 v[220:223], v143 offset:51200
	ds_read_b128 v[230:233], v143 offset:52224
	ds_read_b128 v[234:237], v143 offset:53248
	ds_read_b128 v[238:241], v143 offset:54272
	ds_read_b128 v[242:245], v143 offset:55296
	ds_read_b128 v[246:249], v143 offset:56320
	global_load_lds_dwordx4 v146, s[98:99]
	s_add_i32 m0, s21, 0x2000
	s_add_u32 s30, s30, 0x40080
	s_addc_u32 s31, s31, 0
	s_add_i32 s20, s20, s57
	global_load_lds_dwordx4 v128, s[98:99]
	s_mov_b32 m0, s20
	s_nop 0
	global_load_lds_dwordx4 v146, s[30:31]
	s_add_i32 m0, s20, 0x2000
	s_nop 0
	global_load_lds_dwordx4 v128, s[30:31]
	s_mov_b32 m0, s66
	s_nop 0
	global_load_lds_dwordx4 v132, s[100:101]
	s_mov_b32 m0, s67
	s_nop 0
	global_load_lds_dwordx4 v130, s[100:101]
	s_waitcnt vmcnt(8)
	s_waitcnt lgkmcnt(0)
	s_barrier
	s_setprio 1
	s_waitcnt lgkmcnt(0)
	v_mfma_f32_16x16x32_bf16 v[60:63], v[158:161], v[190:193], v[60:63]
	v_mfma_f32_16x16x32_bf16 v[52:55], v[166:169], v[190:193], v[52:55]
	v_mfma_f32_16x16x32_bf16 v[44:47], v[158:161], v[220:223], v[44:47]
	v_mfma_f32_16x16x32_bf16 v[36:39], v[166:169], v[220:223], v[36:39]
	v_mfma_f32_16x16x32_bf16 v[28:31], v[158:161], v[234:237], v[28:31]
	v_mfma_f32_16x16x32_bf16 v[20:23], v[166:169], v[234:237], v[20:23]
	v_mfma_f32_16x16x32_bf16 v[12:15], v[158:161], v[242:245], v[12:15]
	v_mfma_f32_16x16x32_bf16 v[4:7], v[166:169], v[242:245], v[4:7]
	v_mfma_f32_16x16x32_bf16 v[60:63], v[162:165], v[194:197], v[60:63]
	v_mfma_f32_16x16x32_bf16 v[52:55], v[170:173], v[194:197], v[52:55]
	v_mfma_f32_16x16x32_bf16 v[44:47], v[162:165], v[230:233], v[44:47]
	v_mfma_f32_16x16x32_bf16 v[36:39], v[170:173], v[230:233], v[36:39]
	v_mfma_f32_16x16x32_bf16 v[28:31], v[162:165], v[238:241], v[28:31]
	v_mfma_f32_16x16x32_bf16 v[20:23], v[170:173], v[238:241], v[20:23]
	v_mfma_f32_16x16x32_bf16 v[12:15], v[162:165], v[246:249], v[12:15]
	v_mfma_f32_16x16x32_bf16 v[4:7], v[170:173], v[246:249], v[4:7]
	s_setprio 0
	s_setprio 1
	v_mfma_f32_16x16x32_bf16 v[56:59], v[174:177], v[190:193], v[56:59]
	v_mfma_f32_16x16x32_bf16 v[48:51], v[182:185], v[190:193], v[48:51]
	v_mfma_f32_16x16x32_bf16 v[40:43], v[174:177], v[220:223], v[40:43]
	v_mfma_f32_16x16x32_bf16 v[32:35], v[182:185], v[220:223], v[32:35]
	v_mfma_f32_16x16x32_bf16 v[24:27], v[174:177], v[234:237], v[24:27]
	v_mfma_f32_16x16x32_bf16 v[16:19], v[182:185], v[234:237], v[16:19]
	v_mfma_f32_16x16x32_bf16 v[8:11], v[174:177], v[242:245], v[8:11]
	v_mfma_f32_16x16x32_bf16 v[0:3], v[182:185], v[242:245], v[0:3]
	v_mfma_f32_16x16x32_bf16 v[56:59], v[178:181], v[194:197], v[56:59]
	v_mfma_f32_16x16x32_bf16 v[48:51], v[186:189], v[194:197], v[48:51]
	v_mfma_f32_16x16x32_bf16 v[40:43], v[178:181], v[230:233], v[40:43]
	v_mfma_f32_16x16x32_bf16 v[32:35], v[186:189], v[230:233], v[32:35]
	v_mfma_f32_16x16x32_bf16 v[24:27], v[178:181], v[238:241], v[24:27]
	v_mfma_f32_16x16x32_bf16 v[16:19], v[186:189], v[238:241], v[16:19]
	v_mfma_f32_16x16x32_bf16 v[8:11], v[178:181], v[246:249], v[8:11]
	v_mfma_f32_16x16x32_bf16 v[0:3], v[186:189], v[246:249], v[0:3]
	s_setprio 0
	s_barrier
	s_add_i32 s69, s69, 2
	s_add_u32 s52, s52, 0x100
	s_addc_u32 s53, s53, 0
	s_add_u32 s43, s43, 0x100
	s_addc_u32 s45, s45, 0
	s_cmp_gt_u32 s69, 13
	s_cbranch_scc0 .LBB0_471
	s_and_b64 vcc, exec, s[22:23]
	s_cbranch_vccz .LBB0_474
	s_barrier

; __global__ void __launch_bounds__(NTHREADS) mega(Args a) {
	.amdhsa_kernel _Z4mega4Args
		.amdhsa_group_segment_fixed_size 0
		.amdhsa_private_segment_fixed_size 0
		.amdhsa_kernarg_size 464
		.amdhsa_user_sgpr_count 2
		.amdhsa_user_sgpr_dispatch_ptr 0
		.amdhsa_user_sgpr_queue_ptr 0
		.amdhsa_user_sgpr_kernarg_segment_ptr 1
		.amdhsa_user_sgpr_dispatch_id 0
		.amdhsa_user_sgpr_kernarg_preload_length 0
		.amdhsa_user_sgpr_kernarg_preload_offset 0
		.amdhsa_user_sgpr_private_segment_size 0
		.amdhsa_uses_dynamic_stack 0
		.amdhsa_enable_private_segment 0
		.amdhsa_system_sgpr_workgroup_id_x 1
		.amdhsa_system_sgpr_workgroup_id_y 0
		.amdhsa_system_sgpr_workgroup_id_z 0
		.amdhsa_system_sgpr_workgroup_info 0
		.amdhsa_system_vgpr_workitem_id 2
		.amdhsa_next_free_vgpr 256
		.amdhsa_next_free_sgpr 102
		.amdhsa_accum_offset 256
		.amdhsa_reserve_vcc 1
		.amdhsa_float_round_mode_32 0
		.amdhsa_float_round_mode_16_64 0
		.amdhsa_float_denorm_mode_32 3
		.amdhsa_float_denorm_mode_16_64 3
		.amdhsa_dx10_clamp 1
		.amdhsa_ieee_mode 1
		.amdhsa_fp16_overflow 0
		.amdhsa_tg_split 0
		.amdhsa_exception_fp_ieee_invalid_op 0
		.amdhsa_exception_fp_denorm_src 0
		.amdhsa_exception_fp_ieee_div_zero 0
		.amdhsa_exception_fp_ieee_overflow 0
		.amdhsa_exception_fp_ieee_underflow 0
		.amdhsa_exception_fp_ieee_inexact 0
		.amdhsa_exception_int_div_zero 0
	.end_amdhsa_kernel

; __global__ void __launch_bounds__(NTHREADS) mega(Args a) {
amdhsa.kernels:
  - .agpr_count:     0
    .args:
      - .offset:         0
        .size:           208
        .value_kind:     by_value
      - .offset:         208
        .size:           4
        .value_kind:     hidden_block_count_x
      - .offset:         212
        .size:           4
        .value_kind:     hidden_block_count_y
      - .offset:         216
        .size:           4
        .value_kind:     hidden_block_count_z
      - .offset:         220
        .size:           2
        .value_kind:     hidden_group_size_x
      - .offset:         222
        .size:           2
        .value_kind:     hidden_group_size_y
      - .offset:         224
        .size:           2
        .value_kind:     hidden_group_size_z
      - .offset:         226
        .size:           2
        .value_kind:     hidden_remainder_x
      - .offset:         228
        .size:           2
        .value_kind:     hidden_remainder_y
      - .offset:         230
        .size:           2
        .value_kind:     hidden_remainder_z
      - .offset:         248
        .size:           8
        .value_kind:     hidden_global_offset_x
      - .offset:         256
        .size:           8
        .value_kind:     hidden_global_offset_y
      - .offset:         264
        .size:           8
        .value_kind:     hidden_global_offset_z
      - .offset:         272
        .size:           2
        .value_kind:     hidden_grid_dims
      - .offset:         296
        .size:           8
        .value_kind:     hidden_multigrid_sync_arg
      - .offset:         328
        .size:           4
        .value_kind:     hidden_dynamic_lds_size
    .group_segment_fixed_size: 0
    .kernarg_segment_align: 8
    .kernarg_segment_size: 464
    .language:       OpenCL C
    .language_version:
      - 2
      - 0
    .max_flat_workgroup_size: 512
    .name:           _Z4mega4Args
    .private_segment_fixed_size: 0
    .sgpr_count:     108
    .sgpr_spill_count: 258
    .symbol:         _Z4mega4Args.kd
    .uniform_work_group_size: 1
    .uses_dynamic_stack: false
    .vgpr_count:     256
    .vgpr_spill_count: 0
    .wavefront_size: 64
